# SwiGLU epilogue: n=0/n=1 bf16 pieces exchanged with v_permlane16_swap, 16 dwordx2 stores -> 8 dwordx4 per lane
# speedup vs baseline: 1.0169x; 1.0055x over previous
; template <int EPI>
; DI void gemm_unit(const GemmP& g, int pm, int pn) {
;     ...
;     const int hc0 = pn * 128 + wc * 32 + fq * 4;
; #pragma unroll
;     for (int ai = 0; ai < 2; ++ai)
; #pragma unroll
;       for (int m = 0; m < 4; ++m) {
;         u16* rowp = g.Cb + (size_t)(row0 + ai * 128 + m * 16) * g.ldc + hc0;
; #pragma unroll
;         for (int n = 0; n < 2; ++n) {
;           const f32x4 gv = acc[ai][0][m][n], uv = acc[ai][1][m][n];
;           float hv[4];
; #pragma unroll
;           for (int e = 0; e < 4; ++e) hv[e] = gv[e] * __builtin_amdgcn_rcpf(1.f + __builtin_amdgcn_exp2f(-LOG2E * gv[e])) * uv[e];
;           uint2 o; o.x = pk2(hv[0], hv[1]); o.y = pk2(hv[2], hv[3]);
;           *(uint2*)(rowp + n * 16) = o;
;         }
;       }
.LBB0_150:
	s_or_b64 exec, exec, s[10:11]
	v_mul_f32_e32 v136, 0xbfb8aa3b, v122
	v_mul_f32_e32 v137, 0xbfb8aa3b, v123
	v_exp_f32_e32 v136, v136
	v_exp_f32_e32 v137, v137
	v_lshlrev_b32_e32 v0, 5, v143
	v_lshlrev_b32_e32 v130, 2, v144
	v_add_f32_e32 v136, 1.0, v136
	v_add_f32_e32 v137, 1.0, v137
	v_rcp_f32_e32 v136, v136
	v_rcp_f32_e32 v137, v137
	s_lshl_b32 s9, s22, 7
	v_or3_b32 v132, s9, v0, v130
	v_or_b32_e32 v0, s8, v142
	v_pk_mul_f32 v[122:123], v[122:123], v[136:137]
	v_add_u32_e32 v0, v0, v145
	v_pk_mul_f32 v[122:123], v[122:123], v[126:127]
	v_mul_f32_e32 v126, 0xbfb8aa3b, v124
	v_mul_f32_e32 v127, 0xbfb8aa3b, v125
	v_exp_f32_e32 v126, v126
	v_exp_f32_e32 v127, v127
	v_ashrrev_i32_e32 v133, 31, v132
	v_mov_b64_e32 v[130:131], s[6:7]
	v_add_f32_e32 v126, 1.0, v126
	v_add_f32_e32 v127, 1.0, v127
	v_rcp_f32_e32 v126, v126
	v_rcp_f32_e32 v127, v127
	s_movk_i32 s10, 0x2c00
	v_mad_i64_i32 v[134:135], s[8:9], v0, s10, v[130:131]
	v_pk_mul_f32 v[124:125], v[124:125], v[126:127]
	v_lshlrev_b64 v[132:133], 1, v[132:133]
	v_and_b32_e32 v146, 1, v144
	v_mul_u32_u24_e32 v146, 24, v146
	v_add_u32_e32 v132, v132, v146
	v_pk_mul_f32 v[124:125], v[124:125], v[128:129]
	v_lshl_add_u64 v[134:135], v[134:135], 0, v[132:133]
	v_cvt_pk_bf16_f32 v148, v122, v123
	v_cvt_pk_bf16_f32 v149, v124, v125
	v_mul_f32_e32 v122, 0xbfb8aa3b, v114
	v_mul_f32_e32 v123, 0xbfb8aa3b, v115
	v_exp_f32_e32 v122, v122
	v_exp_f32_e32 v123, v123
	v_add_f32_e32 v122, 1.0, v122
	v_add_f32_e32 v123, 1.0, v123
	v_rcp_f32_e32 v122, v122
	v_rcp_f32_e32 v123, v123
	s_nop 0
	v_pk_mul_f32 v[114:115], v[114:115], v[122:123]
	s_nop 0
	v_pk_mul_f32 v[114:115], v[114:115], v[118:119]
	v_mul_f32_e32 v118, 0xbfb8aa3b, v116
	v_mul_f32_e32 v119, 0xbfb8aa3b, v117
	v_exp_f32_e32 v118, v118
	v_exp_f32_e32 v119, v119
	v_cvt_pk_bf16_f32 v150, v114, v115
	v_add_f32_e32 v118, 1.0, v118
	v_add_f32_e32 v119, 1.0, v119
	v_rcp_f32_e32 v118, v118
	v_rcp_f32_e32 v119, v119
	s_nop 0
	v_pk_mul_f32 v[116:117], v[116:117], v[118:119]
	s_nop 0
	v_pk_mul_f32 v[116:117], v[116:117], v[120:121]
	s_nop 0
	v_cvt_pk_bf16_f32 v151, v116, v117
	v_mul_f32_e32 v116, 0xbfb8aa3b, v106
	v_mul_f32_e32 v117, 0xbfb8aa3b, v107
	v_exp_f32_e32 v116, v116
	v_exp_f32_e32 v117, v117
	v_permlane16_swap_b32_e32 v148, v150
	v_permlane16_swap_b32_e32 v149, v151
	s_nop 0
	global_store_dwordx4 v[134:135], v[148:151], off
	v_or_b32_e32 v114, 16, v0
	v_add_f32_e32 v116, 1.0, v116
	v_add_f32_e32 v117, 1.0, v117
	v_rcp_f32_e32 v116, v116
	v_rcp_f32_e32 v117, v117
	v_mad_i64_i32 v[114:115], s[8:9], v114, s10, v[130:131]
	v_lshl_add_u64 v[114:115], v[114:115], 0, v[132:133]
	v_pk_mul_f32 v[106:107], v[106:107], v[116:117]
	s_nop 0
	v_pk_mul_f32 v[106:107], v[106:107], v[110:111]
	v_mul_f32_e32 v110, 0xbfb8aa3b, v108
	v_mul_f32_e32 v111, 0xbfb8aa3b, v109
	v_exp_f32_e32 v110, v110
	v_exp_f32_e32 v111, v111
	v_cvt_pk_bf16_f32 v152, v106, v107
	v_add_f32_e32 v110, 1.0, v110
	v_add_f32_e32 v111, 1.0, v111
	v_rcp_f32_e32 v110, v110
	v_rcp_f32_e32 v111, v111
	s_nop 0
	v_pk_mul_f32 v[108:109], v[108:109], v[110:111]
	s_nop 0
	v_pk_mul_f32 v[108:109], v[108:109], v[112:113]
	s_nop 0
	v_cvt_pk_bf16_f32 v153, v108, v109
	v_mul_f32_e32 v106, 0xbfb8aa3b, v98
	v_mul_f32_e32 v107, 0xbfb8aa3b, v99
	v_exp_f32_e32 v106, v106
	v_exp_f32_e32 v107, v107
	v_add_f32_e32 v106, 1.0, v106
	v_add_f32_e32 v107, 1.0, v107
	v_rcp_f32_e32 v106, v106
	v_rcp_f32_e32 v107, v107
	s_nop 0
	v_pk_mul_f32 v[98:99], v[98:99], v[106:107]
	s_nop 0
	v_pk_mul_f32 v[98:99], v[98:99], v[102:103]
	v_mul_f32_e32 v102, 0xbfb8aa3b, v100
	v_mul_f32_e32 v103, 0xbfb8aa3b, v101
	v_exp_f32_e32 v102, v102
	v_exp_f32_e32 v103, v103
	v_cvt_pk_bf16_f32 v154, v98, v99
	v_add_f32_e32 v102, 1.0, v102
	v_add_f32_e32 v103, 1.0, v103
	v_rcp_f32_e32 v102, v102
	v_rcp_f32_e32 v103, v103
	s_nop 0
	v_pk_mul_f32 v[100:101], v[100:101], v[102:103]
	s_nop 0
	v_pk_mul_f32 v[100:101], v[100:101], v[104:105]
	s_nop 0
	v_cvt_pk_bf16_f32 v155, v100, v101
	v_mul_f32_e32 v100, 0xbfb8aa3b, v90
	v_mul_f32_e32 v101, 0xbfb8aa3b, v91
	v_exp_f32_e32 v100, v100
	v_exp_f32_e32 v101, v101
	v_permlane16_swap_b32_e32 v152, v154
	v_permlane16_swap_b32_e32 v153, v155
	s_nop 0
	global_store_dwordx4 v[114:115], v[152:155], off
	v_or_b32_e32 v98, 32, v0
	v_add_f32_e32 v100, 1.0, v100
	v_add_f32_e32 v101, 1.0, v101
	v_rcp_f32_e32 v100, v100
	v_rcp_f32_e32 v101, v101
	v_mad_i64_i32 v[98:99], s[8:9], v98, s10, v[130:131]
	v_lshl_add_u64 v[98:99], v[98:99], 0, v[132:133]
	v_pk_mul_f32 v[90:91], v[90:91], v[100:101]
	s_nop 0
	v_pk_mul_f32 v[90:91], v[90:91], v[94:95]
	v_mul_f32_e32 v94, 0xbfb8aa3b, v92
	v_mul_f32_e32 v95, 0xbfb8aa3b, v93
	v_exp_f32_e32 v94, v94
	v_exp_f32_e32 v95, v95
	v_cvt_pk_bf16_f32 v156, v90, v91
	v_add_f32_e32 v94, 1.0, v94
	v_add_f32_e32 v95, 1.0, v95
	v_rcp_f32_e32 v94, v94
	v_rcp_f32_e32 v95, v95
	s_nop 0
	v_pk_mul_f32 v[92:93], v[92:93], v[94:95]
	s_nop 0
	v_pk_mul_f32 v[92:93], v[92:93], v[96:97]
	s_nop 0
	v_cvt_pk_bf16_f32 v157, v92, v93
	v_mul_f32_e32 v90, 0xbfb8aa3b, v82
	v_mul_f32_e32 v91, 0xbfb8aa3b, v83
	v_exp_f32_e32 v90, v90
	v_exp_f32_e32 v91, v91
	v_add_f32_e32 v90, 1.0, v90
	v_add_f32_e32 v91, 1.0, v91
	v_rcp_f32_e32 v90, v90
	v_rcp_f32_e32 v91, v91
	s_nop 0
	v_pk_mul_f32 v[82:83], v[82:83], v[90:91]
	s_nop 0
	v_pk_mul_f32 v[82:83], v[82:83], v[86:87]
	v_mul_f32_e32 v86, 0xbfb8aa3b, v84
	v_mul_f32_e32 v87, 0xbfb8aa3b, v85
	v_exp_f32_e32 v86, v86
	v_exp_f32_e32 v87, v87
	v_cvt_pk_bf16_f32 v158, v82, v83
	v_add_f32_e32 v86, 1.0, v86
	v_add_f32_e32 v87, 1.0, v87
	v_rcp_f32_e32 v86, v86
	v_rcp_f32_e32 v87, v87
	s_nop 0
	v_pk_mul_f32 v[84:85], v[84:85], v[86:87]
	s_nop 0
	v_pk_mul_f32 v[84:85], v[84:85], v[88:89]
; template <int EPI>
; DI void gemm_unit(const GemmP& g, int pm, int pn) {
;     ...
;     const int hc0 = pn * 128 + wc * 32 + fq * 4;
; #pragma unroll
;     for (int ai = 0; ai < 2; ++ai)
; #pragma unroll
;       for (int m = 0; m < 4; ++m) {
;         u16* rowp = g.Cb + (size_t)(row0 + ai * 128 + m * 16) * g.ldc + hc0;
; #pragma unroll
;         for (int n = 0; n < 2; ++n) {
;           const f32x4 gv = acc[ai][0][m][n], uv = acc[ai][1][m][n];
;           float hv[4];
; #pragma unroll
;           for (int e = 0; e < 4; ++e) hv[e] = gv[e] * __builtin_amdgcn_rcpf(1.f + __builtin_amdgcn_exp2f(-LOG2E * gv[e])) * uv[e];
;           uint2 o; o.x = pk2(hv[0], hv[1]); o.y = pk2(hv[2], hv[3]);
;           *(uint2*)(rowp + n * 16) = o;
;         }
;       }
	s_nop 0
	v_cvt_pk_bf16_f32 v159, v84, v85
	v_mul_f32_e32 v84, 0xbfb8aa3b, v74
	v_mul_f32_e32 v85, 0xbfb8aa3b, v75
	v_exp_f32_e32 v84, v84
	v_exp_f32_e32 v85, v85
	v_permlane16_swap_b32_e32 v156, v158
	v_permlane16_swap_b32_e32 v157, v159
	s_nop 0
	global_store_dwordx4 v[98:99], v[156:159], off
	v_or_b32_e32 v82, 48, v0
	v_add_f32_e32 v84, 1.0, v84
	v_add_f32_e32 v85, 1.0, v85
	v_rcp_f32_e32 v84, v84
	v_rcp_f32_e32 v85, v85
	v_mad_i64_i32 v[82:83], s[8:9], v82, s10, v[130:131]
	v_lshl_add_u64 v[82:83], v[82:83], 0, v[132:133]
	v_pk_mul_f32 v[74:75], v[74:75], v[84:85]
	s_nop 0
	v_pk_mul_f32 v[74:75], v[74:75], v[78:79]
	v_mul_f32_e32 v78, 0xbfb8aa3b, v76
	v_mul_f32_e32 v79, 0xbfb8aa3b, v77
	v_exp_f32_e32 v78, v78
	v_exp_f32_e32 v79, v79
	v_cvt_pk_bf16_f32 v160, v74, v75
	v_add_f32_e32 v78, 1.0, v78
	v_add_f32_e32 v79, 1.0, v79
	v_rcp_f32_e32 v78, v78
	v_rcp_f32_e32 v79, v79
	s_nop 0
	v_pk_mul_f32 v[76:77], v[76:77], v[78:79]
	s_nop 0
	v_pk_mul_f32 v[76:77], v[76:77], v[80:81]
	s_nop 0
	v_cvt_pk_bf16_f32 v161, v76, v77
	v_mul_f32_e32 v74, 0xbfb8aa3b, v66
	v_mul_f32_e32 v75, 0xbfb8aa3b, v67
	v_exp_f32_e32 v74, v74
	v_exp_f32_e32 v75, v75
	v_add_f32_e32 v74, 1.0, v74
	v_add_f32_e32 v75, 1.0, v75
	v_rcp_f32_e32 v74, v74
	v_rcp_f32_e32 v75, v75
	s_nop 0
	v_pk_mul_f32 v[66:67], v[66:67], v[74:75]
	s_nop 0
	v_pk_mul_f32 v[66:67], v[66:67], v[70:71]
	v_mul_f32_e32 v70, 0xbfb8aa3b, v68
	v_mul_f32_e32 v71, 0xbfb8aa3b, v69
	v_exp_f32_e32 v70, v70
	v_exp_f32_e32 v71, v71
	v_cvt_pk_bf16_f32 v162, v66, v67
	v_add_f32_e32 v70, 1.0, v70
	v_add_f32_e32 v71, 1.0, v71
	v_rcp_f32_e32 v70, v70
	v_rcp_f32_e32 v71, v71
	s_nop 0
	v_pk_mul_f32 v[68:69], v[68:69], v[70:71]
	s_nop 0
	v_pk_mul_f32 v[68:69], v[68:69], v[72:73]
	s_nop 0
	v_cvt_pk_bf16_f32 v163, v68, v69
	v_mul_f32_e32 v68, 0xbfb8aa3b, v58
	v_mul_f32_e32 v69, 0xbfb8aa3b, v59
	v_exp_f32_e32 v68, v68
	v_exp_f32_e32 v69, v69
	v_permlane16_swap_b32_e32 v160, v162
	v_permlane16_swap_b32_e32 v161, v163
	s_nop 0
	global_store_dwordx4 v[82:83], v[160:163], off
	v_add_u32_e32 v66, 0x80, v0
	v_add_f32_e32 v68, 1.0, v68
	v_add_f32_e32 v69, 1.0, v69
	v_rcp_f32_e32 v68, v68
	v_rcp_f32_e32 v69, v69
	v_mad_i64_i32 v[66:67], s[8:9], v66, s10, v[130:131]
	v_lshl_add_u64 v[66:67], v[66:67], 0, v[132:133]
	v_pk_mul_f32 v[58:59], v[58:59], v[68:69]
	s_nop 0
	v_pk_mul_f32 v[58:59], v[58:59], v[62:63]
	v_mul_f32_e32 v62, 0xbfb8aa3b, v60
	v_mul_f32_e32 v63, 0xbfb8aa3b, v61
	v_exp_f32_e32 v62, v62
	v_exp_f32_e32 v63, v63
	v_cvt_pk_bf16_f32 v164, v58, v59
	v_add_f32_e32 v62, 1.0, v62
	v_add_f32_e32 v63, 1.0, v63
	v_rcp_f32_e32 v62, v62
	v_rcp_f32_e32 v63, v63
	s_nop 0
	v_pk_mul_f32 v[60:61], v[60:61], v[62:63]
	s_nop 0
	v_pk_mul_f32 v[60:61], v[60:61], v[64:65]
	s_nop 0
	v_cvt_pk_bf16_f32 v165, v60, v61
	v_mul_f32_e32 v58, 0xbfb8aa3b, v50
	v_mul_f32_e32 v59, 0xbfb8aa3b, v51
	v_exp_f32_e32 v58, v58
	v_exp_f32_e32 v59, v59
	v_add_f32_e32 v58, 1.0, v58
	v_add_f32_e32 v59, 1.0, v59
	v_rcp_f32_e32 v58, v58
	v_rcp_f32_e32 v59, v59
	s_nop 0
	v_pk_mul_f32 v[50:51], v[50:51], v[58:59]
	s_nop 0
	v_pk_mul_f32 v[50:51], v[50:51], v[54:55]
	v_mul_f32_e32 v54, 0xbfb8aa3b, v52
	v_mul_f32_e32 v55, 0xbfb8aa3b, v53
	v_exp_f32_e32 v54, v54
	v_exp_f32_e32 v55, v55
	v_cvt_pk_bf16_f32 v166, v50, v51
	v_add_f32_e32 v54, 1.0, v54
	v_add_f32_e32 v55, 1.0, v55
	v_rcp_f32_e32 v54, v54
	v_rcp_f32_e32 v55, v55
	s_nop 0
	v_pk_mul_f32 v[52:53], v[52:53], v[54:55]
	s_nop 0
	v_pk_mul_f32 v[52:53], v[52:53], v[56:57]
	s_nop 0
	v_cvt_pk_bf16_f32 v167, v52, v53
	v_mul_f32_e32 v52, 0xbfb8aa3b, v42
	v_mul_f32_e32 v53, 0xbfb8aa3b, v43
	v_exp_f32_e32 v52, v52
	v_exp_f32_e32 v53, v53
	v_permlane16_swap_b32_e32 v164, v166
	v_permlane16_swap_b32_e32 v165, v167
	s_nop 0
	global_store_dwordx4 v[66:67], v[164:167], off
	v_add_u32_e32 v50, 0x90, v0
	v_add_f32_e32 v52, 1.0, v52
	v_add_f32_e32 v53, 1.0, v53
	v_rcp_f32_e32 v52, v52
	v_rcp_f32_e32 v53, v53
	v_mad_i64_i32 v[50:51], s[8:9], v50, s10, v[130:131]
	v_lshl_add_u64 v[50:51], v[50:51], 0, v[132:133]
	v_pk_mul_f32 v[42:43], v[42:43], v[52:53]
	s_nop 0
	v_pk_mul_f32 v[42:43], v[42:43], v[46:47]
	v_mul_f32_e32 v46, 0xbfb8aa3b, v44
	v_mul_f32_e32 v47, 0xbfb8aa3b, v45
	v_exp_f32_e32 v46, v46
	v_exp_f32_e32 v47, v47
	v_cvt_pk_bf16_f32 v168, v42, v43
	v_add_f32_e32 v46, 1.0, v46
	v_add_f32_e32 v47, 1.0, v47
	v_rcp_f32_e32 v46, v46
	v_rcp_f32_e32 v47, v47
	s_nop 0
	v_pk_mul_f32 v[44:45], v[44:45], v[46:47]
	s_nop 0
	v_pk_mul_f32 v[44:45], v[44:45], v[48:49]
; #define BID opqs((int)blockIdx.x)
; template <int EPI>
; DI void gemm_unit(const GemmP& g, int pm, int pn) {
;     ...
;     const int hc0 = pn * 128 + wc * 32 + fq * 4;
; #pragma unroll
;     for (int ai = 0; ai < 2; ++ai)
; #pragma unroll
;       for (int m = 0; m < 4; ++m) {
;         u16* rowp = g.Cb + (size_t)(row0 + ai * 128 + m * 16) * g.ldc + hc0;
; #pragma unroll
;         for (int n = 0; n < 2; ++n) {
;           const f32x4 gv = acc[ai][0][m][n], uv = acc[ai][1][m][n];
;           float hv[4];
; #pragma unroll
;           for (int e = 0; e < 4; ++e) hv[e] = gv[e] * __builtin_amdgcn_rcpf(1.f + __builtin_amdgcn_exp2f(-LOG2E * gv[e])) * uv[e];
;           uint2 o; o.x = pk2(hv[0], hv[1]); o.y = pk2(hv[2], hv[3]);
;           *(uint2*)(rowp + n * 16) = o;
;         }
;       }
; template <int E1, int E2>
; DI void gemm_phase2(const GemmP& g1, const GemmP& g2, char* smem) {
;     ...
;   for (int L = BID; L < n1 + n2; L += gridDim.x) {
;     int pm, pn;
;     if (L < n1) { unit_of(L, g1.Mt, g1.Nt, pm, pn); gemm_unit<E1>(g1, pm, pn); }
;     else { unit_of(L - n1, g2.Mt, g2.Nt, pm, pn); gemm_unit<E2>(g2, pm, pn); }
;   }
	s_nop 0
	v_cvt_pk_bf16_f32 v169, v44, v45
	v_mul_f32_e32 v42, 0xbfb8aa3b, v34
	v_mul_f32_e32 v43, 0xbfb8aa3b, v35
	v_exp_f32_e32 v42, v42
	v_exp_f32_e32 v43, v43
	v_add_f32_e32 v42, 1.0, v42
	v_add_f32_e32 v43, 1.0, v43
	v_rcp_f32_e32 v42, v42
	v_rcp_f32_e32 v43, v43
	s_nop 0
	v_pk_mul_f32 v[34:35], v[34:35], v[42:43]
	s_nop 0
	v_pk_mul_f32 v[34:35], v[34:35], v[38:39]
	v_mul_f32_e32 v38, 0xbfb8aa3b, v36
	v_mul_f32_e32 v39, 0xbfb8aa3b, v37
	v_exp_f32_e32 v38, v38
	v_exp_f32_e32 v39, v39
	v_cvt_pk_bf16_f32 v170, v34, v35
	v_add_f32_e32 v38, 1.0, v38
	v_add_f32_e32 v39, 1.0, v39
	v_rcp_f32_e32 v38, v38
	v_rcp_f32_e32 v39, v39
	s_nop 0
	v_pk_mul_f32 v[36:37], v[36:37], v[38:39]
	s_nop 0
	v_pk_mul_f32 v[36:37], v[36:37], v[40:41]
	s_nop 0
	v_cvt_pk_bf16_f32 v171, v36, v37
	v_mul_f32_e32 v36, 0xbfb8aa3b, v26
	v_mul_f32_e32 v37, 0xbfb8aa3b, v27
	v_exp_f32_e32 v36, v36
	v_exp_f32_e32 v37, v37
	v_permlane16_swap_b32_e32 v168, v170
	v_permlane16_swap_b32_e32 v169, v171
	s_nop 0
	global_store_dwordx4 v[50:51], v[168:171], off
	v_add_u32_e32 v34, 0xa0, v0
	v_add_f32_e32 v36, 1.0, v36
	v_add_f32_e32 v37, 1.0, v37
	v_rcp_f32_e32 v36, v36
	v_rcp_f32_e32 v37, v37
	v_mad_i64_i32 v[34:35], s[8:9], v34, s10, v[130:131]
	v_lshl_add_u64 v[34:35], v[34:35], 0, v[132:133]
	v_pk_mul_f32 v[26:27], v[26:27], v[36:37]
	v_add_u32_e32 v0, 0xb0, v0
	v_pk_mul_f32 v[26:27], v[26:27], v[30:31]
	v_mul_f32_e32 v30, 0xbfb8aa3b, v28
	v_mul_f32_e32 v31, 0xbfb8aa3b, v29
	v_exp_f32_e32 v30, v30
	v_exp_f32_e32 v31, v31
	v_cvt_pk_bf16_f32 v172, v26, v27
	v_add_f32_e32 v30, 1.0, v30
	v_add_f32_e32 v31, 1.0, v31
	v_rcp_f32_e32 v30, v30
	v_rcp_f32_e32 v31, v31
	s_nop 0
	v_pk_mul_f32 v[28:29], v[28:29], v[30:31]
	s_nop 0
	v_pk_mul_f32 v[28:29], v[28:29], v[32:33]
	s_nop 0
	v_cvt_pk_bf16_f32 v173, v28, v29
	v_mul_f32_e32 v26, 0xbfb8aa3b, v18
	v_mul_f32_e32 v27, 0xbfb8aa3b, v19
	v_exp_f32_e32 v26, v26
	v_exp_f32_e32 v27, v27
	v_add_f32_e32 v26, 1.0, v26
	v_add_f32_e32 v27, 1.0, v27
	v_rcp_f32_e32 v26, v26
	v_rcp_f32_e32 v27, v27
	s_nop 0
	v_pk_mul_f32 v[18:19], v[18:19], v[26:27]
	s_nop 0
	v_pk_mul_f32 v[18:19], v[18:19], v[22:23]
	v_mul_f32_e32 v22, 0xbfb8aa3b, v20
	v_mul_f32_e32 v23, 0xbfb8aa3b, v21
	v_exp_f32_e32 v22, v22
	v_exp_f32_e32 v23, v23
	v_cvt_pk_bf16_f32 v174, v18, v19
	v_add_f32_e32 v22, 1.0, v22
	v_add_f32_e32 v23, 1.0, v23
	v_rcp_f32_e32 v22, v22
	v_rcp_f32_e32 v23, v23
	s_nop 0
	v_pk_mul_f32 v[20:21], v[20:21], v[22:23]
	s_nop 0
	v_pk_mul_f32 v[20:21], v[20:21], v[24:25]
	s_nop 0
	v_cvt_pk_bf16_f32 v175, v20, v21
	s_nop 1
	v_permlane16_swap_b32_e32 v172, v174
	v_permlane16_swap_b32_e32 v173, v175
	s_nop 0
	global_store_dwordx4 v[34:35], v[172:175], off
	v_mad_i64_i32 v[18:19], s[8:9], v0, s10, v[130:131]
	v_mul_f32_e32 v0, 0xbfb8aa3b, v10
	v_exp_f32_e32 v0, v0
	v_lshl_add_u64 v[18:19], v[18:19], 0, v[132:133]
	v_readlane_b32 s8, v254, 1
	s_add_i32 s13, s13, s8
	v_add_f32_e32 v0, 1.0, v0
	v_rcp_f32_e32 v20, v0
	v_mul_f32_e32 v0, 0xbfb8aa3b, v11
	v_exp_f32_e32 v0, v0
	s_cmpk_gt_i32 s13, 0xaff
	v_readlane_b32 s9, v254, 2
	v_add_f32_e32 v0, 1.0, v0
	v_rcp_f32_e32 v21, v0
	v_mul_f32_e32 v0, 0xbfb8aa3b, v12
	v_exp_f32_e32 v0, v0
	v_pk_mul_f32 v[10:11], v[10:11], v[20:21]
	s_nop 0
	v_pk_mul_f32 v[10:11], v[10:11], v[14:15]
	v_add_f32_e32 v0, 1.0, v0
	v_rcp_f32_e32 v14, v0
	v_mul_f32_e32 v0, 0xbfb8aa3b, v13
	v_exp_f32_e32 v0, v0
	v_cvt_pk_bf16_f32 v176, v10, v11
	v_add_f32_e32 v0, 1.0, v0
	v_rcp_f32_e32 v15, v0
	v_mul_f32_e32 v0, 0xbfb8aa3b, v2
	v_exp_f32_e32 v0, v0
	v_pk_mul_f32 v[12:13], v[12:13], v[14:15]
	s_nop 0
	v_pk_mul_f32 v[12:13], v[12:13], v[16:17]
	v_add_f32_e32 v0, 1.0, v0
	v_cvt_pk_bf16_f32 v177, v12, v13
	v_rcp_f32_e32 v10, v0
	v_mul_f32_e32 v0, 0xbfb8aa3b, v3
	v_exp_f32_e32 v0, v0
	s_nop 0
	v_add_f32_e32 v0, 1.0, v0
	v_rcp_f32_e32 v11, v0
	v_mul_f32_e32 v0, 0xbfb8aa3b, v4
	v_exp_f32_e32 v0, v0
	v_pk_mul_f32 v[2:3], v[2:3], v[10:11]
	s_nop 0
	v_pk_mul_f32 v[2:3], v[2:3], v[6:7]
	v_add_f32_e32 v0, 1.0, v0
	v_rcp_f32_e32 v6, v0
	v_mul_f32_e32 v0, 0xbfb8aa3b, v5
	v_exp_f32_e32 v0, v0
	v_cvt_pk_bf16_f32 v178, v2, v3
	v_add_f32_e32 v0, 1.0, v0
	v_rcp_f32_e32 v7, v0
	s_nop 0
	v_pk_mul_f32 v[4:5], v[4:5], v[6:7]
	s_nop 0
	v_pk_mul_f32 v[4:5], v[4:5], v[8:9]
	s_nop 0
	v_cvt_pk_bf16_f32 v179, v4, v5
	s_nop 1
	v_permlane16_swap_b32_e32 v176, v178
	v_permlane16_swap_b32_e32 v177, v179
	s_nop 0
	global_store_dwordx4 v[18:19], v[176:179], off
	s_cbranch_scc1 .LBB0_157
